# GB1: grid barrier: non-leader workgroups poll the cross-XCC release generation directly (skip the per-XCC relay hop) in the 8 per-layer barrier instances; on top of BE1
# speedup vs baseline: 1.0027x; 1.0007x over previous
.LBB0_236:
	s_or_b64 exec, exec, s[16:17]
	v_cvt_f32_u32_e32 v7, v5
	s_waitcnt vmcnt(0)
	v_readfirstlane_b32 s5, v6
	v_sub_u32_e32 v6, 0, v5
	v_rcp_iflag_f32_e32 v7, v7
	v_add_u32_e32 v8, s5, v2
	v_mul_f32_e32 v7, 0x4f7ffffe, v7
	v_cvt_u32_f32_e32 v7, v7
	v_mul_lo_u32 v2, v6, v7
	v_mul_hi_u32 v2, v7, v2
	v_add_u32_e32 v2, v7, v2
	v_mul_hi_u32 v2, v8, v2
	v_mul_lo_u32 v6, v2, v5
	v_sub_u32_e32 v6, v8, v6
	v_add_u32_e32 v7, 1, v2
	v_cmp_ge_u32_e32 vcc, v6, v5
	s_nop 1
	v_cndmask_b32_e32 v2, v2, v7, vcc
	v_sub_u32_e32 v7, v6, v5
	v_cndmask_b32_e32 v6, v6, v7, vcc
	v_add_u32_e32 v7, 1, v2
	v_cmp_ge_u32_e32 vcc, v6, v5
	v_add_u32_e32 v6, 1, v8
	s_nop 0
	v_cndmask_b32_e32 v2, v2, v7, vcc
	v_mul_lo_u32 v7, v5, v2
	v_add_u32_e32 v5, v7, v5
	v_cmp_ne_u32_e32 vcc, v6, v5
	s_and_saveexec_b64 s[6:7], vcc
	s_xor_b64 s[18:19], exec, s[6:7]
	s_cbranch_execz .LBB0_250
	v_readlane_b32 s6, v255, 4
	v_readlane_b32 s7, v255, 5
	s_waitcnt lgkmcnt(0)
	s_nop 3
	global_load_dword v4, v3, s[6:7] sc1
	s_waitcnt vmcnt(0)
	v_cmp_eq_u32_e32 vcc, v4, v2
	s_and_saveexec_b64 s[16:17], vcc
	s_cbranch_execz .LBB0_249
	s_mov_b32 s5, 1
	s_mov_b64 s[20:21], 0
	s_branch .LBB0_240

.LBB0_1199:
	s_or_b64 exec, exec, s[16:17]
	v_cvt_f32_u32_e32 v7, v5
	s_waitcnt vmcnt(0)
	v_readfirstlane_b32 s4, v6
	v_sub_u32_e32 v6, 0, v5
	v_rcp_iflag_f32_e32 v7, v7
	v_add_u32_e32 v8, s4, v2
	v_mul_f32_e32 v7, 0x4f7ffffe, v7
	v_cvt_u32_f32_e32 v7, v7
	v_mul_lo_u32 v2, v6, v7
	v_mul_hi_u32 v2, v7, v2
	v_add_u32_e32 v2, v7, v2
	v_mul_hi_u32 v2, v8, v2
	v_mul_lo_u32 v6, v2, v5
	v_sub_u32_e32 v6, v8, v6
	v_add_u32_e32 v7, 1, v2
	v_cmp_ge_u32_e32 vcc, v6, v5
	s_nop 1
	v_cndmask_b32_e32 v2, v2, v7, vcc
	v_sub_u32_e32 v7, v6, v5
	v_cndmask_b32_e32 v6, v6, v7, vcc
	v_add_u32_e32 v7, 1, v2
	v_cmp_ge_u32_e32 vcc, v6, v5
	v_add_u32_e32 v6, 1, v8
	s_nop 0
	v_cndmask_b32_e32 v2, v2, v7, vcc
	v_mul_lo_u32 v7, v5, v2
	v_add_u32_e32 v5, v7, v5
	v_cmp_ne_u32_e32 vcc, v6, v5
	s_and_saveexec_b64 s[4:5], vcc
	s_xor_b64 s[18:19], exec, s[4:5]
	s_cbranch_execz .LBB0_1213
	v_readlane_b32 s4, v255, 4
	v_readlane_b32 s5, v255, 5
	s_waitcnt lgkmcnt(0)
	s_nop 3
	global_load_dword v4, v3, s[4:5] sc1
	s_waitcnt vmcnt(0)
	v_cmp_eq_u32_e32 vcc, v4, v2
	s_and_saveexec_b64 s[16:17], vcc
	s_cbranch_execz .LBB0_1212
	s_mov_b32 s4, 1
	s_mov_b64 s[20:21], 0
	s_branch .LBB0_1203
